# v76 + mLSTM scan: per-chunk gate cumsum / cummax wave scans done with DPP row_shr/row_bcast instead of 12 serialized ds_bpermute round trips
# speedup vs baseline: 1.0074x; 1.0074x over previous
.LBB0_204:
	s_or_b64 exec, exec, s[86:87]
	s_andn2_b64 vcc, exec, s[82:83]
	s_waitcnt lgkmcnt(0)
	s_barrier
	s_cbranch_vccnz .LBB0_208
	ds_read_b64 v[72:73], v159
	ds_read_b64 v[76:77], v160
	s_waitcnt lgkmcnt(1)
	v_add_f32_e32 v73, v72, v73
	v_mov_b32_e32 v75, v73
	s_nop 1
	v_add_f32_dpp v75, v75, v75 row_shr:1 row_mask:0xf bank_mask:0xf
	s_nop 1
	v_add_f32_dpp v75, v75, v75 row_shr:2 row_mask:0xf bank_mask:0xf
	s_nop 1
	v_add_f32_dpp v75, v75, v75 row_shr:4 row_mask:0xf bank_mask:0xf
	s_nop 1
	v_add_f32_dpp v75, v75, v75 row_shr:8 row_mask:0xf bank_mask:0xf
	s_nop 1
	v_add_f32_dpp v75, v75, v75 row_bcast:15 row_mask:0xa bank_mask:0xf
	s_nop 1
	v_add_f32_dpp v75, v75, v75 row_bcast:31 row_mask:0xc bank_mask:0xf
	s_waitcnt lgkmcnt(0)
	v_sub_f32_e32 v73, v75, v73
	v_add_f32_e32 v74, v72, v73
	v_pk_add_f32 v[76:77], v[76:77], v[74:75] neg_lo:[0,1] neg_hi:[0,1]
	ds_bpermute_b32 v72, v162, v75
	v_max_f32_e32 v73, v76, v77
	s_nop 1
	v_max_f32_dpp v73, v73, v73 row_shr:1 row_mask:0xf bank_mask:0xf
	s_nop 1
	v_max_f32_dpp v73, v73, v73 row_shr:2 row_mask:0xf bank_mask:0xf
	s_nop 1
	v_max_f32_dpp v73, v73, v73 row_shr:4 row_mask:0xf bank_mask:0xf
	s_nop 1
	v_max_f32_dpp v73, v73, v73 row_shr:8 row_mask:0xf bank_mask:0xf
	s_nop 1
	v_max_f32_dpp v73, v73, v73 row_bcast:15 row_mask:0xa bank_mask:0xf
	s_nop 1
	v_max_f32_dpp v73, v73, v73 row_bcast:31 row_mask:0xc bank_mask:0xf
	ds_bpermute_b32 v78, v161, v73
	v_max_f32_e32 v73, v73, v73
	v_max_f32_e32 v79, v135, v135
	v_max_f32_e32 v79, v79, v73
	v_add_f32_e32 v75, v75, v79
	s_waitcnt lgkmcnt(0)
	v_cndmask_b32_e64 v78, v78, v218, s[4:5]
	v_max3_f32 v78, v135, v78, v76
	v_add_f32_e32 v74, v74, v78
	ds_bpermute_b32 v73, v162, v79
	v_mul_f32_e32 v74, 0xbfb8aa3b, v74
	v_mul_f32_e32 v75, 0xbfb8aa3b, v75
	v_exp_f32_e32 v74, v74
	v_exp_f32_e32 v75, v75
	ds_write_b64 v163, v[76:77]
	ds_write_b64 v164, v[78:79]
	v_sub_f32_e32 v80, v135, v78
	v_sub_f32_e32 v81, v135, v79
	ds_write_b64 v166, v[74:75]
	s_waitcnt lgkmcnt(3)
	v_sub_f32_e32 v74, v76, v73
	v_sub_f32_e32 v75, v77, v73
	v_mul_f32_e32 v80, 0x3fb8aa3b, v80
	v_mul_f32_e32 v81, 0x3fb8aa3b, v81
	v_mul_f32_e32 v74, 0x3fb8aa3b, v74
	v_mul_f32_e32 v75, 0x3fb8aa3b, v75
	v_exp_f32_e32 v80, v80
	v_exp_f32_e32 v81, v81
	v_exp_f32_e32 v74, v74
	v_exp_f32_e32 v75, v75
	ds_write_b64 v165, v[80:81]
	ds_write_b64 v167, v[74:75]
	s_and_saveexec_b64 s[86:87], s[4:5]
	s_cbranch_execz .LBB0_207
	v_sub_f32_e32 v74, v135, v73
	v_mul_f32_e32 v74, 0x3fb8aa3b, v74
	v_exp_f32_e32 v74, v74
	v_mov_b32_e32 v75, s33
	ds_write_b32 v75, v74
